# hyconv staging loop fully unrolled with the next iteration's global loads issued before the current compute (two register sets, shifted vmcnt)
# baseline (speedup 1.0000x reference)
; __device__ __forceinline__ float bf2f(bf16_t h) { return __uint_as_float(((unsigned)h) << 16); }
; __device__ __forceinline__ void phase_hyconv(CP& p, char* smem) {
;     ...
;       for (int i = 0; i < 8; ++i) {
;         const int q = tid + 256 * i; const int b = q >> 8, l8 = q & 255; const int m1 = l8 >> 3, m2 = (l8 & 7) * 8;
;         const int l0 = l8 * 8;
;         const bf16_t* z2 = p.vvT + (size_t)c * 16384 + b * 2048;
;         const bf16_t* zv = p.vvT + (size_t)(1024 + c) * 16384 + b * 2048;
;         const uint4 u2 = *(const uint4*)(z2 + l0), uv = *(const uint4*)(zv + l0);
;         float e2[10], ev[10];
;         const int lp = l0 > 0 ? l0 - 1 : 0, ln = l0 + 8 < 2048 ? l0 + 8 : 2047;
;         const float pm = l0 > 0 ? 1.f : 0.f, nm = l0 + 8 < 2048 ? 1.f : 0.f;
;         const bf16_t q2p = z2[lp], qvp = zv[lp], q2n = z2[ln], qvn = zv[ln];
;         e2[0] = bf2f(q2p) * pm; ev[0] = bf2f(qvp) * pm;
;         e2[9] = bf2f(q2n) * nm; ev[9] = bf2f(qvn) * nm;
;         const unsigned w2[4] = {u2.x, u2.y, u2.z, u2.w}, wv[4] = {uv.x, uv.y, uv.z, uv.w};
; #pragma unroll
;         for (int j = 0; j < 4; ++j) {
;           e2[1 + 2 * j] = __uint_as_float(w2[j] << 16); e2[2 + 2 * j] = __uint_as_float(w2[j] & 0xffff0000u);
;           ev[1 + 2 * j] = __uint_as_float(wv[j] << 16); ev[2 + 2 * j] = __uint_as_float(wv[j] & 0xffff0000u);
.LBB0_2852:
	s_movk_i32 s51, 0x0
	v_add_u32_e32 v15, s51, v101
	v_ashrrev_i32_e32 v17, 8, v15
	v_add_u32_e32 v15, 0x100, v15
	v_lshlrev_b32_e32 v16, 11, v17
	v_add_u32_e32 v18, v127, v17
	v_ashrrev_i32_e32 v15, 8, v15
	v_ashrrev_i32_e32 v17, 31, v16
	v_mad_u64_u32 v[32:33], s[74:75], v18, s3, v[100:101]
	v_lshlrev_b32_e32 v18, 11, v15
	v_lshlrev_b64 v[16:17], 1, v[16:17]
	v_ashrrev_i32_e32 v19, 31, v18
	v_add_u32_e32 v15, v127, v15
	v_lshl_add_u64 v[20:21], s[46:47], 0, v[16:17]
	v_lshl_add_u64 v[16:17], s[48:49], 0, v[16:17]
	v_lshlrev_b64 v[18:19], 1, v[18:19]
	v_mad_u64_u32 v[34:35], s[74:75], v15, s3, v[100:101]
	v_lshl_add_u64 v[22:23], v[20:21], 0, v[118:119]
	v_lshl_add_u64 v[24:25], v[16:17], 0, v[118:119]
	v_lshl_add_u64 v[26:27], v[20:21], 0, v[120:121]
	v_lshl_add_u64 v[28:29], v[16:17], 0, v[120:121]
	v_lshl_add_u64 v[20:21], v[20:21], 0, v[122:123]
	v_lshl_add_u64 v[16:17], v[16:17], 0, v[122:123]
	v_lshl_add_u64 v[30:31], s[46:47], 0, v[18:19]
	v_lshl_add_u64 v[36:37], s[48:49], 0, v[18:19]
	global_load_ushort v15, v[26:27], off
	global_load_ushort v33, v[28:29], off
	global_load_ushort v35, v[20:21], off
	global_load_ushort v40, v[16:17], off
	s_nop 0
	global_load_dwordx4 v[16:19], v[22:23], off
	s_nop 0
	global_load_dwordx4 v[20:23], v[24:25], off
	v_lshl_add_u64 v[24:25], v[30:31], 0, v[118:119]
	v_lshl_add_u64 v[28:29], v[36:37], 0, v[118:119]
	v_lshl_add_u64 v[26:27], v[30:31], 0, v[120:121]
	v_lshl_add_u64 v[38:39], v[36:37], 0, v[120:121]
	v_lshl_add_u64 v[30:31], v[30:31], 0, v[122:123]
	v_lshl_add_u64 v[36:37], v[36:37], 0, v[122:123]
	global_load_ushort v41, v[26:27], off
	s_nop 0
	global_load_ushort v38, v[38:39], off
	s_nop 0
	global_load_ushort v39, v[30:31], off
	s_nop 0
	global_load_ushort v36, v[36:37], off
	s_nop 0
	global_load_dwordx4 v[24:27], v[24:25], off
	s_nop 0
	global_load_dwordx4 v[28:31], v[28:29], off
	s_movk_i32 s51, 0x200
	v_add_u32_e32 v155, s51, v101
	v_ashrrev_i32_e32 v157, 8, v155
	v_add_u32_e32 v155, 0x100, v155
	v_lshlrev_b32_e32 v156, 11, v157
	v_add_u32_e32 v158, v127, v157
	v_ashrrev_i32_e32 v155, 8, v155
	v_ashrrev_i32_e32 v157, 31, v156
	v_mad_u64_u32 v[172:173], s[74:75], v158, s3, v[100:101]
	v_lshlrev_b32_e32 v158, 11, v155
	v_lshlrev_b64 v[156:157], 1, v[156:157]
	v_ashrrev_i32_e32 v159, 31, v158
	v_add_u32_e32 v155, v127, v155
	v_lshl_add_u64 v[160:161], s[46:47], 0, v[156:157]
	v_lshl_add_u64 v[156:157], s[48:49], 0, v[156:157]
	v_lshlrev_b64 v[158:159], 1, v[158:159]
	v_mad_u64_u32 v[174:175], s[74:75], v155, s3, v[100:101]
	v_lshl_add_u64 v[162:163], v[160:161], 0, v[118:119]
	v_lshl_add_u64 v[164:165], v[156:157], 0, v[118:119]
	v_lshl_add_u64 v[166:167], v[160:161], 0, v[120:121]
	v_lshl_add_u64 v[168:169], v[156:157], 0, v[120:121]
	v_lshl_add_u64 v[160:161], v[160:161], 0, v[122:123]
	v_lshl_add_u64 v[156:157], v[156:157], 0, v[122:123]
	v_lshl_add_u64 v[170:171], s[46:47], 0, v[158:159]
	v_lshl_add_u64 v[176:177], s[48:49], 0, v[158:159]
	global_load_ushort v155, v[166:167], off
	global_load_ushort v173, v[168:169], off
	global_load_ushort v175, v[160:161], off
	global_load_ushort v180, v[156:157], off
	s_nop 0
	global_load_dwordx4 v[156:159], v[162:163], off
	s_nop 0
	global_load_dwordx4 v[160:163], v[164:165], off
	v_lshl_add_u64 v[164:165], v[170:171], 0, v[118:119]
	v_lshl_add_u64 v[168:169], v[176:177], 0, v[118:119]
	v_lshl_add_u64 v[166:167], v[170:171], 0, v[120:121]
	v_lshl_add_u64 v[178:179], v[176:177], 0, v[120:121]
	v_lshl_add_u64 v[170:171], v[170:171], 0, v[122:123]
	v_lshl_add_u64 v[176:177], v[176:177], 0, v[122:123]
	global_load_ushort v181, v[166:167], off
	s_nop 0
	global_load_ushort v178, v[178:179], off
	s_nop 0
	global_load_ushort v179, v[170:171], off
	s_nop 0
	global_load_ushort v176, v[176:177], off
	s_nop 0
	global_load_dwordx4 v[164:167], v[164:165], off
	s_nop 0
	global_load_dwordx4 v[168:171], v[168:169], off
	s_waitcnt vmcnt(23)
	v_lshlrev_b32_e32 v15, 16, v15
	s_waitcnt vmcnt(22)
	v_lshlrev_b32_e32 v33, 16, v33
	v_mul_f32_e32 v15, v125, v15
	s_waitcnt vmcnt(20)
	v_lshlrev_b32_e32 v37, 16, v40
	s_waitcnt vmcnt(19)
	v_lshlrev_b32_e32 v40, 16, v16
	v_and_b32_e32 v16, 0xffff0000, v16
	s_waitcnt vmcnt(18)
	v_lshlrev_b32_e32 v42, 16, v20
	v_and_b32_e32 v20, 0xffff0000, v20
	v_lshlrev_b32_e32 v43, 16, v17
	v_and_b32_e32 v17, 0xffff0000, v17
	v_lshlrev_b32_e32 v44, 16, v21
	v_and_b32_e32 v21, 0xffff0000, v21
	v_lshlrev_b32_e32 v45, 16, v18
	v_and_b32_e32 v18, 0xffff0000, v18
	v_lshlrev_b32_e32 v46, 16, v22
	v_and_b32_e32 v22, 0xffff0000, v22
	v_lshlrev_b32_e32 v47, 16, v19
	v_lshlrev_b32_e32 v48, 16, v23
	v_and_b32_e32 v19, 0xffff0000, v19
	v_and_b32_e32 v23, 0xffff0000, v23
	v_mul_f32_e32 v33, v125, v33
	v_mul_f32_e32 v49, v11, v16
	v_mul_f32_e32 v50, v5, v20
	v_mul_f32_e32 v51, v11, v43
	v_mul_f32_e32 v52, v11, v17
	v_mul_f32_e32 v53, v5, v44
	v_mul_f32_e32 v54, v5, v21
	v_mul_f32_e32 v55, v11, v45
	v_mul_f32_e32 v56, v11, v18
	v_mul_f32_e32 v57, v5, v46
	v_mul_f32_e32 v58, v5, v22
	v_mul_f32_e32 v59, v11, v47
	v_mul_f32_e32 v61, v5, v48
	s_waitcnt vmcnt(17)
	v_lshlrev_b32_e32 v41, 16, v41
	s_waitcnt vmcnt(16)
	v_lshlrev_b32_e32 v38, 16, v38
	s_waitcnt vmcnt(13)
	v_lshlrev_b32_e32 v65, 16, v25
	v_and_b32_e32 v25, 0xffff0000, v25
	s_waitcnt vmcnt(12)
; __device__ __forceinline__ unsigned pack2(float a, float b) { unsigned r; asm("v_cvt_pk_bf16_f32 %0, %1, %2" : "=v"(r) : "v"(a), "v"(b)); return r; }
; __device__ __forceinline__ void phase_hyconv(CP& p, char* smem) {
;     ...
;         const unsigned w2[4] = {u2.x, u2.y, u2.z, u2.w}, wv[4] = {uv.x, uv.y, uv.z, uv.w};
; #pragma unroll
;         for (int j = 0; j < 4; ++j) {
;           e2[1 + 2 * j] = __uint_as_float(w2[j] << 16); e2[2 + 2 * j] = __uint_as_float(w2[j] & 0xffff0000u);
;           ev[1 + 2 * j] = __uint_as_float(wv[j] << 16); ev[2 + 2 * j] = __uint_as_float(wv[j] & 0xffff0000u);
;         }
;         unsigned o[4];
; #pragma unroll
;         for (int j = 0; j < 4; ++j) {
;           const float xa = a0 * e2[2 * j] + a1 * e2[2 * j + 1] + a2 * e2[2 * j + 2] + ab;
;           const float xb = a0 * e2[2 * j + 1] + a1 * e2[2 * j + 2] + a2 * e2[2 * j + 3] + ab;
;           const float ya = v0 * ev[2 * j] + v1 * ev[2 * j + 1] + v2 * ev[2 * j + 2] + vb;
;           const float yb = v0 * ev[2 * j + 1] + v1 * ev[2 * j + 2] + v2 * ev[2 * j + 3] + vb;
;           o[j] = pack2(xa * ya, xb * yb);
;         }
;         uint4 ou; ou.x = o[0]; ou.y = o[1]; ou.z = o[2]; ou.w = o[3];
;         *(uint4*)(Vl + (8 + m1 * 8 + b) * 80 + m2) = ou;
	v_lshlrev_b32_e32 v66, 16, v29
	v_and_b32_e32 v29, 0xffff0000, v29
	v_lshlrev_b32_e32 v35, 16, v35
	v_mul_f32_e32 v60, v11, v19
	v_mul_f32_e32 v62, v5, v23
	v_lshlrev_b32_e32 v63, 16, v24
	v_and_b32_e32 v24, 0xffff0000, v24
	v_lshlrev_b32_e32 v64, 16, v28
	v_and_b32_e32 v28, 0xffff0000, v28
	v_lshlrev_b32_e32 v67, 16, v26
	v_and_b32_e32 v26, 0xffff0000, v26
	v_lshlrev_b32_e32 v68, 16, v30
	v_and_b32_e32 v30, 0xffff0000, v30
	v_lshlrev_b32_e32 v69, 16, v27
	v_and_b32_e32 v27, 0xffff0000, v27
	v_lshlrev_b32_e32 v70, 16, v31
	v_and_b32_e32 v31, 0xffff0000, v31
	v_mul_f32_e32 v15, v3, v15
	v_fmac_f32_e32 v49, v3, v40
	v_mul_f32_e32 v33, v13, v33
	v_fmac_f32_e32 v50, v13, v42
	v_fmac_f32_e32 v51, v3, v16
	v_fmac_f32_e32 v52, v3, v43
	v_fmac_f32_e32 v53, v13, v20
	v_fmac_f32_e32 v54, v13, v44
	v_fmac_f32_e32 v55, v3, v17
	v_fmac_f32_e32 v56, v3, v45
	v_fmac_f32_e32 v57, v13, v21
	v_fmac_f32_e32 v58, v13, v46
	v_fmac_f32_e32 v59, v3, v18
	v_fmac_f32_e32 v61, v13, v22
	v_mul_f32_e32 v41, v125, v41
	v_mul_f32_e32 v38, v125, v38
	v_mul_f32_e32 v73, v11, v65
	v_mul_f32_e32 v74, v11, v25
	v_mul_f32_e32 v75, v5, v66
	v_mul_f32_e32 v76, v5, v29
	v_mul_f32_e32 v35, v126, v35
	v_mul_f32_e32 v37, v126, v37
	v_lshlrev_b32_e32 v39, 16, v39
	v_lshlrev_b32_e32 v36, 16, v36
	v_fmac_f32_e32 v60, v3, v47
	v_fmac_f32_e32 v62, v13, v48
	v_mul_f32_e32 v71, v11, v24
	v_mul_f32_e32 v72, v5, v28
	v_mul_f32_e32 v77, v11, v67
	v_mul_f32_e32 v78, v11, v26
	v_mul_f32_e32 v79, v5, v68
	v_mul_f32_e32 v80, v5, v30
	v_mul_f32_e32 v81, v11, v69
	v_mul_f32_e32 v82, v11, v27
	v_mul_f32_e32 v83, v5, v70
	v_mul_f32_e32 v84, v5, v31
	v_fmac_f32_e32 v15, v11, v40
	v_fmac_f32_e32 v49, v12, v43
	v_fmac_f32_e32 v33, v5, v42
	v_fmac_f32_e32 v50, v10, v44
	v_fmac_f32_e32 v51, v12, v17
	v_fmac_f32_e32 v52, v12, v45
	v_fmac_f32_e32 v53, v10, v21
	v_fmac_f32_e32 v54, v10, v46
	v_fmac_f32_e32 v55, v12, v18
	v_fmac_f32_e32 v56, v12, v47
	v_fmac_f32_e32 v57, v10, v22
	v_fmac_f32_e32 v58, v10, v48
	v_fmac_f32_e32 v59, v12, v19
	v_fmac_f32_e32 v61, v10, v23
	v_mul_f32_e32 v21, v3, v41
	v_mul_f32_e32 v22, v13, v38
	v_fmac_f32_e32 v73, v3, v24
	v_fmac_f32_e32 v74, v3, v65
	v_fmac_f32_e32 v75, v13, v28
	v_fmac_f32_e32 v76, v13, v66
	v_mul_f32_e32 v39, v126, v39
	v_mul_f32_e32 v36, v126, v36
	v_fmac_f32_e32 v60, v12, v35
	v_fmac_f32_e32 v62, v10, v37
	v_fmac_f32_e32 v71, v3, v63
	v_fmac_f32_e32 v72, v13, v64
	v_fmac_f32_e32 v77, v3, v25
	v_fmac_f32_e32 v78, v3, v67
	v_fmac_f32_e32 v79, v13, v29
	v_fmac_f32_e32 v80, v13, v68
	v_fmac_f32_e32 v81, v3, v26
	v_fmac_f32_e32 v82, v3, v69
	v_fmac_f32_e32 v83, v13, v30
	v_fmac_f32_e32 v84, v13, v70
	v_fmac_f32_e32 v15, v12, v16
	v_add_f32_e32 v16, v4, v49
	v_fmac_f32_e32 v33, v10, v20
	v_add_f32_e32 v17, v14, v50
	v_add_f32_e32 v18, v4, v51
	v_add_f32_e32 v19, v4, v52
	v_add_f32_e32 v20, v14, v53
	v_add_f32_e32 v23, v14, v54
	v_add_f32_e32 v35, v4, v55
	v_add_f32_e32 v37, v4, v56
	v_add_f32_e32 v38, v14, v57
	v_add_f32_e32 v40, v14, v58
	v_add_f32_e32 v41, v4, v59
	v_add_f32_e32 v43, v14, v61
	v_fmac_f32_e32 v21, v11, v63
	v_fmac_f32_e32 v22, v5, v64
	v_fmac_f32_e32 v73, v12, v25
	v_fmac_f32_e32 v74, v12, v67
	v_fmac_f32_e32 v75, v10, v29
	v_fmac_f32_e32 v76, v10, v68
	v_add_f32_e32 v42, v4, v60
	v_add_f32_e32 v44, v14, v62
	v_fmac_f32_e32 v71, v12, v65
	v_fmac_f32_e32 v72, v10, v66
	v_fmac_f32_e32 v77, v12, v26
	v_fmac_f32_e32 v78, v12, v69
	v_fmac_f32_e32 v79, v10, v30
	v_fmac_f32_e32 v80, v10, v70
	v_fmac_f32_e32 v81, v12, v27
	v_fmac_f32_e32 v82, v12, v39
	v_fmac_f32_e32 v83, v10, v31
	v_fmac_f32_e32 v84, v10, v36
	v_add_f32_e32 v15, v4, v15
	v_add_f32_e32 v25, v14, v33
	v_mul_f32_e32 v16, v16, v17
	v_mul_f32_e32 v17, v18, v20
	v_mul_f32_e32 v18, v19, v23
	v_mul_f32_e32 v19, v35, v38
	v_mul_f32_e32 v20, v37, v40
	v_mul_f32_e32 v23, v41, v43
	v_fmac_f32_e32 v21, v12, v24
	v_fmac_f32_e32 v22, v10, v28
	v_add_f32_e32 v28, v4, v73
	v_add_f32_e32 v29, v4, v74
	v_add_f32_e32 v30, v14, v75
	v_add_f32_e32 v31, v14, v76
	v_mul_f32_e32 v26, v42, v44
	v_add_f32_e32 v24, v4, v71
	v_add_f32_e32 v27, v14, v72
	v_add_f32_e32 v33, v4, v77
	v_add_f32_e32 v35, v4, v78
	v_add_f32_e32 v36, v14, v79
	v_add_f32_e32 v37, v14, v80
	v_add_f32_e32 v38, v4, v81
	v_add_f32_e32 v39, v4, v82
	v_add_f32_e32 v40, v14, v83
	v_add_f32_e32 v41, v14, v84
	v_mul_f32_e32 v15, v15, v25
	v_cvt_pk_bf16_f32 v17, v17, v18
	v_cvt_pk_bf16_f32 v18, v19, v20
	v_cvt_pk_bf16_f32 v19, v23, v26
	v_add_f32_e32 v20, v4, v21
	v_add_f32_e32 v21, v14, v22
	v_mul_f32_e32 v22, v28, v30
	v_mul_f32_e32 v23, v29, v31
	v_mul_f32_e32 v24, v24, v27
	v_mul_f32_e32 v25, v33, v36
	v_mul_f32_e32 v26, v35, v37
	v_mul_f32_e32 v27, v38, v40
	v_mul_f32_e32 v28, v39, v41
	v_cvt_pk_bf16_f32 v16, v15, v16
	v_mul_f32_e32 v15, v20, v21
	v_cvt_pk_bf16_f32 v21, v22, v23
	v_cvt_pk_bf16_f32 v22, v25, v26
	v_cvt_pk_bf16_f32 v23, v27, v28
	ds_write_b128 v32, v[16:19] offset:33024
	v_cvt_pk_bf16_f32 v20, v15, v24
	ds_write_b128 v34, v[20:23] offset:33024
	s_movk_i32 s51, 0x400
	v_add_u32_e32 v15, s51, v101
	v_ashrrev_i32_e32 v17, 8, v15
	v_add_u32_e32 v15, 0x100, v15
	v_lshlrev_b32_e32 v16, 11, v17
	v_add_u32_e32 v18, v127, v17
	v_ashrrev_i32_e32 v15, 8, v15
	v_ashrrev_i32_e32 v17, 31, v16
	v_mad_u64_u32 v[32:33], s[74:75], v18, s3, v[100:101]
	v_lshlrev_b32_e32 v18, 11, v15
	v_lshlrev_b64 v[16:17], 1, v[16:17]
	v_ashrrev_i32_e32 v19, 31, v18
	v_add_u32_e32 v15, v127, v15
	v_lshl_add_u64 v[20:21], s[46:47], 0, v[16:17]
	v_lshl_add_u64 v[16:17], s[48:49], 0, v[16:17]
	v_lshlrev_b64 v[18:19], 1, v[18:19]
	v_mad_u64_u32 v[34:35], s[74:75], v15, s3, v[100:101]
	v_lshl_add_u64 v[22:23], v[20:21], 0, v[118:119]
	v_lshl_add_u64 v[24:25], v[16:17], 0, v[118:119]
	v_lshl_add_u64 v[26:27], v[20:21], 0, v[120:121]
	v_lshl_add_u64 v[28:29], v[16:17], 0, v[120:121]
	v_lshl_add_u64 v[20:21], v[20:21], 0, v[122:123]
	v_lshl_add_u64 v[16:17], v[16:17], 0, v[122:123]
	v_lshl_add_u64 v[30:31], s[46:47], 0, v[18:19]
	v_lshl_add_u64 v[36:37], s[48:49], 0, v[18:19]
	global_load_ushort v15, v[26:27], off
	global_load_ushort v33, v[28:29], off
	global_load_ushort v35, v[20:21], off
	global_load_ushort v40, v[16:17], off
	s_nop 0
	global_load_dwordx4 v[16:19], v[22:23], off
	s_nop 0
	global_load_dwordx4 v[20:23], v[24:25], off
	v_lshl_add_u64 v[24:25], v[30:31], 0, v[118:119]
	v_lshl_add_u64 v[28:29], v[36:37], 0, v[118:119]
	v_lshl_add_u64 v[26:27], v[30:31], 0, v[120:121]
	v_lshl_add_u64 v[38:39], v[36:37], 0, v[120:121]
	v_lshl_add_u64 v[30:31], v[30:31], 0, v[122:123]
	v_lshl_add_u64 v[36:37], v[36:37], 0, v[122:123]
	global_load_ushort v41, v[26:27], off
	s_nop 0
	global_load_ushort v38, v[38:39], off
	s_nop 0
	global_load_ushort v39, v[30:31], off
	s_nop 0
	global_load_ushort v36, v[36:37], off
	s_nop 0
	global_load_dwordx4 v[24:27], v[24:25], off
	s_nop 0
	global_load_dwordx4 v[28:31], v[28:29], off
	s_waitcnt vmcnt(23)
; __device__ __forceinline__ unsigned pack2(float a, float b) { unsigned r; asm("v_cvt_pk_bf16_f32 %0, %1, %2" : "=v"(r) : "v"(a), "v"(b)); return r; }
; __device__ __forceinline__ float bf2f(bf16_t h) { return __uint_as_float(((unsigned)h) << 16); }
; __device__ __forceinline__ void phase_hyconv(CP& p, char* smem) {
;     ...
;         const int q = tid + 256 * i; const int b = q >> 8, l8 = q & 255; const int m1 = l8 >> 3, m2 = (l8 & 7) * 8;
;         const int l0 = l8 * 8;
;         const bf16_t* z2 = p.vvT + (size_t)c * 16384 + b * 2048;
;         const bf16_t* zv = p.vvT + (size_t)(1024 + c) * 16384 + b * 2048;
;         const uint4 u2 = *(const uint4*)(z2 + l0), uv = *(const uint4*)(zv + l0);
;         float e2[10], ev[10];
;         const int lp = l0 > 0 ? l0 - 1 : 0, ln = l0 + 8 < 2048 ? l0 + 8 : 2047;
;         const float pm = l0 > 0 ? 1.f : 0.f, nm = l0 + 8 < 2048 ? 1.f : 0.f;
;         const bf16_t q2p = z2[lp], qvp = zv[lp], q2n = z2[ln], qvn = zv[ln];
;         e2[0] = bf2f(q2p) * pm; ev[0] = bf2f(qvp) * pm;
;         e2[9] = bf2f(q2n) * nm; ev[9] = bf2f(qvn) * nm;
;         const unsigned w2[4] = {u2.x, u2.y, u2.z, u2.w}, wv[4] = {uv.x, uv.y, uv.z, uv.w};
; #pragma unroll
;         for (int j = 0; j < 4; ++j) {
;           e2[1 + 2 * j] = __uint_as_float(w2[j] << 16); e2[2 + 2 * j] = __uint_as_float(w2[j] & 0xffff0000u);
;           ev[1 + 2 * j] = __uint_as_float(wv[j] << 16); ev[2 + 2 * j] = __uint_as_float(wv[j] & 0xffff0000u);
;         }
;         unsigned o[4];
; #pragma unroll
;         for (int j = 0; j < 4; ++j) {
;           const float xa = a0 * e2[2 * j] + a1 * e2[2 * j + 1] + a2 * e2[2 * j + 2] + ab;
;           const float xb = a0 * e2[2 * j + 1] + a1 * e2[2 * j + 2] + a2 * e2[2 * j + 3] + ab;
;           const float ya = v0 * ev[2 * j] + v1 * ev[2 * j + 1] + v2 * ev[2 * j + 2] + vb;
;           const float yb = v0 * ev[2 * j + 1] + v1 * ev[2 * j + 2] + v2 * ev[2 * j + 3] + vb;
;           o[j] = pack2(xa * ya, xb * yb);
;         }
	v_lshlrev_b32_e32 v155, 16, v155
	s_waitcnt vmcnt(22)
	v_lshlrev_b32_e32 v173, 16, v173
	v_mul_f32_e32 v155, v125, v155
	s_waitcnt vmcnt(20)
	v_lshlrev_b32_e32 v177, 16, v180
	s_waitcnt vmcnt(19)
	v_lshlrev_b32_e32 v180, 16, v156
	v_and_b32_e32 v156, 0xffff0000, v156
	s_waitcnt vmcnt(18)
	v_lshlrev_b32_e32 v182, 16, v160
	v_and_b32_e32 v160, 0xffff0000, v160
	v_lshlrev_b32_e32 v183, 16, v157
	v_and_b32_e32 v157, 0xffff0000, v157
	v_lshlrev_b32_e32 v184, 16, v161
	v_and_b32_e32 v161, 0xffff0000, v161
	v_lshlrev_b32_e32 v185, 16, v158
	v_and_b32_e32 v158, 0xffff0000, v158
	v_lshlrev_b32_e32 v186, 16, v162
	v_and_b32_e32 v162, 0xffff0000, v162
	v_lshlrev_b32_e32 v187, 16, v159
	v_lshlrev_b32_e32 v188, 16, v163
	v_and_b32_e32 v159, 0xffff0000, v159
	v_and_b32_e32 v163, 0xffff0000, v163
	v_mul_f32_e32 v173, v125, v173
	v_mul_f32_e32 v189, v11, v156
	v_mul_f32_e32 v190, v5, v160
	v_mul_f32_e32 v191, v11, v183
	v_mul_f32_e32 v192, v11, v157
	v_mul_f32_e32 v193, v5, v184
	v_mul_f32_e32 v194, v5, v161
	v_mul_f32_e32 v195, v11, v185
	v_mul_f32_e32 v196, v11, v158
	v_mul_f32_e32 v197, v5, v186
	v_mul_f32_e32 v198, v5, v162
	v_mul_f32_e32 v199, v11, v187
	v_mul_f32_e32 v201, v5, v188
	s_waitcnt vmcnt(17)
	v_lshlrev_b32_e32 v181, 16, v181
	s_waitcnt vmcnt(16)
	v_lshlrev_b32_e32 v178, 16, v178
	s_waitcnt vmcnt(13)
	v_lshlrev_b32_e32 v205, 16, v165
	v_and_b32_e32 v165, 0xffff0000, v165
	s_waitcnt vmcnt(12)
	v_lshlrev_b32_e32 v206, 16, v169
	v_and_b32_e32 v169, 0xffff0000, v169
	v_lshlrev_b32_e32 v175, 16, v175
	v_mul_f32_e32 v200, v11, v159
	v_mul_f32_e32 v202, v5, v163
	v_lshlrev_b32_e32 v203, 16, v164
	v_and_b32_e32 v164, 0xffff0000, v164
	v_lshlrev_b32_e32 v204, 16, v168
	v_and_b32_e32 v168, 0xffff0000, v168
	v_lshlrev_b32_e32 v207, 16, v166
	v_and_b32_e32 v166, 0xffff0000, v166
	v_lshlrev_b32_e32 v208, 16, v170
	v_and_b32_e32 v170, 0xffff0000, v170
	v_lshlrev_b32_e32 v209, 16, v167
	v_and_b32_e32 v167, 0xffff0000, v167
	v_lshlrev_b32_e32 v210, 16, v171
	v_and_b32_e32 v171, 0xffff0000, v171
	v_mul_f32_e32 v155, v3, v155
	v_fmac_f32_e32 v189, v3, v180
	v_mul_f32_e32 v173, v13, v173
	v_fmac_f32_e32 v190, v13, v182
	v_fmac_f32_e32 v191, v3, v156
	v_fmac_f32_e32 v192, v3, v183
	v_fmac_f32_e32 v193, v13, v160
	v_fmac_f32_e32 v194, v13, v184
	v_fmac_f32_e32 v195, v3, v157
	v_fmac_f32_e32 v196, v3, v185
	v_fmac_f32_e32 v197, v13, v161
	v_fmac_f32_e32 v198, v13, v186
	v_fmac_f32_e32 v199, v3, v158
	v_fmac_f32_e32 v201, v13, v162
	v_mul_f32_e32 v181, v125, v181
	v_mul_f32_e32 v178, v125, v178
	v_mul_f32_e32 v213, v11, v205
	v_mul_f32_e32 v214, v11, v165
	v_mul_f32_e32 v215, v5, v206
	v_mul_f32_e32 v216, v5, v169
	v_mul_f32_e32 v175, v126, v175
	v_mul_f32_e32 v177, v126, v177
	v_lshlrev_b32_e32 v179, 16, v179
	v_lshlrev_b32_e32 v176, 16, v176
	v_fmac_f32_e32 v200, v3, v187
	v_fmac_f32_e32 v202, v13, v188
	v_mul_f32_e32 v211, v11, v164
	v_mul_f32_e32 v212, v5, v168
	v_mul_f32_e32 v217, v11, v207
	v_mul_f32_e32 v218, v11, v166
	v_mul_f32_e32 v219, v5, v208
	v_mul_f32_e32 v220, v5, v170
	v_mul_f32_e32 v221, v11, v209
	v_mul_f32_e32 v222, v11, v167
	v_mul_f32_e32 v223, v5, v210
	v_mul_f32_e32 v224, v5, v171
	v_fmac_f32_e32 v155, v11, v180
	v_fmac_f32_e32 v189, v12, v183
	v_fmac_f32_e32 v173, v5, v182
	v_fmac_f32_e32 v190, v10, v184
	v_fmac_f32_e32 v191, v12, v157
	v_fmac_f32_e32 v192, v12, v185
	v_fmac_f32_e32 v193, v10, v161
	v_fmac_f32_e32 v194, v10, v186
	v_fmac_f32_e32 v195, v12, v158
	v_fmac_f32_e32 v196, v12, v187
	v_fmac_f32_e32 v197, v10, v162
	v_fmac_f32_e32 v198, v10, v188
	v_fmac_f32_e32 v199, v12, v159
	v_fmac_f32_e32 v201, v10, v163
	v_mul_f32_e32 v161, v3, v181
	v_mul_f32_e32 v162, v13, v178
	v_fmac_f32_e32 v213, v3, v164
	v_fmac_f32_e32 v214, v3, v205
	v_fmac_f32_e32 v215, v13, v168
	v_fmac_f32_e32 v216, v13, v206
	v_mul_f32_e32 v179, v126, v179
	v_mul_f32_e32 v176, v126, v176
	v_fmac_f32_e32 v200, v12, v175
	v_fmac_f32_e32 v202, v10, v177
	v_fmac_f32_e32 v211, v3, v203
	v_fmac_f32_e32 v212, v13, v204
	v_fmac_f32_e32 v217, v3, v165
	v_fmac_f32_e32 v218, v3, v207
	v_fmac_f32_e32 v219, v13, v169
	v_fmac_f32_e32 v220, v13, v208
	v_fmac_f32_e32 v221, v3, v166
	v_fmac_f32_e32 v222, v3, v209
	v_fmac_f32_e32 v223, v13, v170
	v_fmac_f32_e32 v224, v13, v210
	v_fmac_f32_e32 v155, v12, v156
	v_add_f32_e32 v156, v4, v189
	v_fmac_f32_e32 v173, v10, v160
	v_add_f32_e32 v157, v14, v190
	v_add_f32_e32 v158, v4, v191
	v_add_f32_e32 v159, v4, v192
	v_add_f32_e32 v160, v14, v193
	v_add_f32_e32 v163, v14, v194
	v_add_f32_e32 v175, v4, v195
	v_add_f32_e32 v177, v4, v196
	v_add_f32_e32 v178, v14, v197
	v_add_f32_e32 v180, v14, v198
	v_add_f32_e32 v181, v4, v199
	v_add_f32_e32 v183, v14, v201
	v_fmac_f32_e32 v161, v11, v203
	v_fmac_f32_e32 v162, v5, v204
	v_fmac_f32_e32 v213, v12, v165
	v_fmac_f32_e32 v214, v12, v207
	v_fmac_f32_e32 v215, v10, v169
	v_fmac_f32_e32 v216, v10, v208
	v_add_f32_e32 v182, v4, v200
	v_add_f32_e32 v184, v14, v202
	v_fmac_f32_e32 v211, v12, v205
	v_fmac_f32_e32 v212, v10, v206
	v_fmac_f32_e32 v217, v12, v166
	v_fmac_f32_e32 v218, v12, v209
	v_fmac_f32_e32 v219, v10, v170
	v_fmac_f32_e32 v220, v10, v210
	v_fmac_f32_e32 v221, v12, v167
	v_fmac_f32_e32 v222, v12, v179
	v_fmac_f32_e32 v223, v10, v171
	v_fmac_f32_e32 v224, v10, v176
	v_add_f32_e32 v155, v4, v155
	v_add_f32_e32 v165, v14, v173
	v_mul_f32_e32 v156, v156, v157
	v_mul_f32_e32 v157, v158, v160
	v_mul_f32_e32 v158, v159, v163
	v_mul_f32_e32 v159, v175, v178
	v_mul_f32_e32 v160, v177, v180
	v_mul_f32_e32 v163, v181, v183
	v_fmac_f32_e32 v161, v12, v164
	v_fmac_f32_e32 v162, v10, v168
	v_add_f32_e32 v168, v4, v213
	v_add_f32_e32 v169, v4, v214
	v_add_f32_e32 v170, v14, v215
; __device__ __forceinline__ unsigned pack2(float a, float b) { unsigned r; asm("v_cvt_pk_bf16_f32 %0, %1, %2" : "=v"(r) : "v"(a), "v"(b)); return r; }
; __device__ __forceinline__ float bf2f(bf16_t h) { return __uint_as_float(((unsigned)h) << 16); }
; __device__ __forceinline__ void phase_hyconv(CP& p, char* smem) {
;     ...
;         const int q = tid + 256 * i; const int b = q >> 8, l8 = q & 255; const int m1 = l8 >> 3, m2 = (l8 & 7) * 8;
;         const int l0 = l8 * 8;
;         const bf16_t* z2 = p.vvT + (size_t)c * 16384 + b * 2048;
;         const bf16_t* zv = p.vvT + (size_t)(1024 + c) * 16384 + b * 2048;
;         const uint4 u2 = *(const uint4*)(z2 + l0), uv = *(const uint4*)(zv + l0);
;         float e2[10], ev[10];
;         const int lp = l0 > 0 ? l0 - 1 : 0, ln = l0 + 8 < 2048 ? l0 + 8 : 2047;
;         const float pm = l0 > 0 ? 1.f : 0.f, nm = l0 + 8 < 2048 ? 1.f : 0.f;
;         const bf16_t q2p = z2[lp], qvp = zv[lp], q2n = z2[ln], qvn = zv[ln];
;         e2[0] = bf2f(q2p) * pm; ev[0] = bf2f(qvp) * pm;
;         e2[9] = bf2f(q2n) * nm; ev[9] = bf2f(qvn) * nm;
;         const unsigned w2[4] = {u2.x, u2.y, u2.z, u2.w}, wv[4] = {uv.x, uv.y, uv.z, uv.w};
; #pragma unroll
;         for (int j = 0; j < 4; ++j) {
;           e2[1 + 2 * j] = __uint_as_float(w2[j] << 16); e2[2 + 2 * j] = __uint_as_float(w2[j] & 0xffff0000u);
;           ev[1 + 2 * j] = __uint_as_float(wv[j] << 16); ev[2 + 2 * j] = __uint_as_float(wv[j] & 0xffff0000u);
;         }
;         unsigned o[4];
; #pragma unroll
;         for (int j = 0; j < 4; ++j) {
;           const float xa = a0 * e2[2 * j] + a1 * e2[2 * j + 1] + a2 * e2[2 * j + 2] + ab;
;           const float xb = a0 * e2[2 * j + 1] + a1 * e2[2 * j + 2] + a2 * e2[2 * j + 3] + ab;
;           const float ya = v0 * ev[2 * j] + v1 * ev[2 * j + 1] + v2 * ev[2 * j + 2] + vb;
;           const float yb = v0 * ev[2 * j + 1] + v1 * ev[2 * j + 2] + v2 * ev[2 * j + 3] + vb;
;           o[j] = pack2(xa * ya, xb * yb);
;         }
;         uint4 ou; ou.x = o[0]; ou.y = o[1]; ou.z = o[2]; ou.w = o[3];
;         *(uint4*)(Vl + (8 + m1 * 8 + b) * 80 + m2) = ou;
	v_add_f32_e32 v171, v14, v216
	v_mul_f32_e32 v166, v182, v184
	v_add_f32_e32 v164, v4, v211
	v_add_f32_e32 v167, v14, v212
	v_add_f32_e32 v173, v4, v217
	v_add_f32_e32 v175, v4, v218
	v_add_f32_e32 v176, v14, v219
	v_add_f32_e32 v177, v14, v220
	v_add_f32_e32 v178, v4, v221
	v_add_f32_e32 v179, v4, v222
	v_add_f32_e32 v180, v14, v223
	v_add_f32_e32 v181, v14, v224
	v_mul_f32_e32 v155, v155, v165
	v_cvt_pk_bf16_f32 v157, v157, v158
	v_cvt_pk_bf16_f32 v158, v159, v160
	v_cvt_pk_bf16_f32 v159, v163, v166
	v_add_f32_e32 v160, v4, v161
	v_add_f32_e32 v161, v14, v162
	v_mul_f32_e32 v162, v168, v170
	v_mul_f32_e32 v163, v169, v171
	v_mul_f32_e32 v164, v164, v167
	v_mul_f32_e32 v165, v173, v176
	v_mul_f32_e32 v166, v175, v177
	v_mul_f32_e32 v167, v178, v180
	v_mul_f32_e32 v168, v179, v181
	v_cvt_pk_bf16_f32 v156, v155, v156
	v_mul_f32_e32 v155, v160, v161
	v_cvt_pk_bf16_f32 v161, v162, v163
	v_cvt_pk_bf16_f32 v162, v165, v166
	v_cvt_pk_bf16_f32 v163, v167, v168
	ds_write_b128 v172, v[156:159] offset:33024
	v_cvt_pk_bf16_f32 v160, v155, v164
	ds_write_b128 v174, v[160:163] offset:33024
	s_movk_i32 s51, 0x600
	v_add_u32_e32 v155, s51, v101
	v_ashrrev_i32_e32 v157, 8, v155
	v_add_u32_e32 v155, 0x100, v155
	v_lshlrev_b32_e32 v156, 11, v157
	v_add_u32_e32 v158, v127, v157
	v_ashrrev_i32_e32 v155, 8, v155
	v_ashrrev_i32_e32 v157, 31, v156
	v_mad_u64_u32 v[172:173], s[74:75], v158, s3, v[100:101]
	v_lshlrev_b32_e32 v158, 11, v155
	v_lshlrev_b64 v[156:157], 1, v[156:157]
	v_ashrrev_i32_e32 v159, 31, v158
	v_add_u32_e32 v155, v127, v155
	v_lshl_add_u64 v[160:161], s[46:47], 0, v[156:157]
	v_lshl_add_u64 v[156:157], s[48:49], 0, v[156:157]
	v_lshlrev_b64 v[158:159], 1, v[158:159]
	v_mad_u64_u32 v[174:175], s[74:75], v155, s3, v[100:101]
	v_lshl_add_u64 v[162:163], v[160:161], 0, v[118:119]
	v_lshl_add_u64 v[164:165], v[156:157], 0, v[118:119]
	v_lshl_add_u64 v[166:167], v[160:161], 0, v[120:121]
	v_lshl_add_u64 v[168:169], v[156:157], 0, v[120:121]
	v_lshl_add_u64 v[160:161], v[160:161], 0, v[122:123]
	v_lshl_add_u64 v[156:157], v[156:157], 0, v[122:123]
	v_lshl_add_u64 v[170:171], s[46:47], 0, v[158:159]
	v_lshl_add_u64 v[176:177], s[48:49], 0, v[158:159]
	global_load_ushort v155, v[166:167], off
	global_load_ushort v173, v[168:169], off
	global_load_ushort v175, v[160:161], off
	global_load_ushort v180, v[156:157], off
	s_nop 0
	global_load_dwordx4 v[156:159], v[162:163], off
	s_nop 0
	global_load_dwordx4 v[160:163], v[164:165], off
	v_lshl_add_u64 v[164:165], v[170:171], 0, v[118:119]
	v_lshl_add_u64 v[168:169], v[176:177], 0, v[118:119]
	v_lshl_add_u64 v[166:167], v[170:171], 0, v[120:121]
	v_lshl_add_u64 v[178:179], v[176:177], 0, v[120:121]
	v_lshl_add_u64 v[170:171], v[170:171], 0, v[122:123]
	v_lshl_add_u64 v[176:177], v[176:177], 0, v[122:123]
	global_load_ushort v181, v[166:167], off
	s_nop 0
	global_load_ushort v178, v[178:179], off
	s_nop 0
	global_load_ushort v179, v[170:171], off
	s_nop 0
	global_load_ushort v176, v[176:177], off
	s_nop 0
	global_load_dwordx4 v[164:167], v[164:165], off
	s_nop 0
	global_load_dwordx4 v[168:171], v[168:169], off
	s_waitcnt vmcnt(23)
	v_lshlrev_b32_e32 v15, 16, v15
	s_waitcnt vmcnt(22)
	v_lshlrev_b32_e32 v33, 16, v33
	v_mul_f32_e32 v15, v125, v15
	s_waitcnt vmcnt(20)
	v_lshlrev_b32_e32 v37, 16, v40
	s_waitcnt vmcnt(19)
	v_lshlrev_b32_e32 v40, 16, v16
	v_and_b32_e32 v16, 0xffff0000, v16
	s_waitcnt vmcnt(18)
	v_lshlrev_b32_e32 v42, 16, v20
	v_and_b32_e32 v20, 0xffff0000, v20
	v_lshlrev_b32_e32 v43, 16, v17
	v_and_b32_e32 v17, 0xffff0000, v17
	v_lshlrev_b32_e32 v44, 16, v21
	v_and_b32_e32 v21, 0xffff0000, v21
	v_lshlrev_b32_e32 v45, 16, v18
	v_and_b32_e32 v18, 0xffff0000, v18
	v_lshlrev_b32_e32 v46, 16, v22
	v_and_b32_e32 v22, 0xffff0000, v22
	v_lshlrev_b32_e32 v47, 16, v19
	v_lshlrev_b32_e32 v48, 16, v23
	v_and_b32_e32 v19, 0xffff0000, v19
	v_and_b32_e32 v23, 0xffff0000, v23
	v_mul_f32_e32 v33, v125, v33
	v_mul_f32_e32 v49, v11, v16
	v_mul_f32_e32 v50, v5, v20
	v_mul_f32_e32 v51, v11, v43
	v_mul_f32_e32 v52, v11, v17
	v_mul_f32_e32 v53, v5, v44
	v_mul_f32_e32 v54, v5, v21
	v_mul_f32_e32 v55, v11, v45
	v_mul_f32_e32 v56, v11, v18
	v_mul_f32_e32 v57, v5, v46
	v_mul_f32_e32 v58, v5, v22
	v_mul_f32_e32 v59, v11, v47
	v_mul_f32_e32 v61, v5, v48
	s_waitcnt vmcnt(17)
	v_lshlrev_b32_e32 v41, 16, v41
	s_waitcnt vmcnt(16)
	v_lshlrev_b32_e32 v38, 16, v38
	s_waitcnt vmcnt(13)
	v_lshlrev_b32_e32 v65, 16, v25
	v_and_b32_e32 v25, 0xffff0000, v25
	s_waitcnt vmcnt(12)
; __device__ __forceinline__ unsigned pack2(float a, float b) { unsigned r; asm("v_cvt_pk_bf16_f32 %0, %1, %2" : "=v"(r) : "v"(a), "v"(b)); return r; }
; __device__ __forceinline__ float bf2f(bf16_t h) { return __uint_as_float(((unsigned)h) << 16); }
; __device__ __forceinline__ void phase_hyconv(CP& p, char* smem) {
;     ...
;         e2[0] = bf2f(q2p) * pm; ev[0] = bf2f(qvp) * pm;
;         e2[9] = bf2f(q2n) * nm; ev[9] = bf2f(qvn) * nm;
;         const unsigned w2[4] = {u2.x, u2.y, u2.z, u2.w}, wv[4] = {uv.x, uv.y, uv.z, uv.w};
; #pragma unroll
;         for (int j = 0; j < 4; ++j) {
;           e2[1 + 2 * j] = __uint_as_float(w2[j] << 16); e2[2 + 2 * j] = __uint_as_float(w2[j] & 0xffff0000u);
;           ev[1 + 2 * j] = __uint_as_float(wv[j] << 16); ev[2 + 2 * j] = __uint_as_float(wv[j] & 0xffff0000u);
;         }
;         unsigned o[4];
; #pragma unroll
;         for (int j = 0; j < 4; ++j) {
;           const float xa = a0 * e2[2 * j] + a1 * e2[2 * j + 1] + a2 * e2[2 * j + 2] + ab;
;           const float xb = a0 * e2[2 * j + 1] + a1 * e2[2 * j + 2] + a2 * e2[2 * j + 3] + ab;
;           const float ya = v0 * ev[2 * j] + v1 * ev[2 * j + 1] + v2 * ev[2 * j + 2] + vb;
;           const float yb = v0 * ev[2 * j + 1] + v1 * ev[2 * j + 2] + v2 * ev[2 * j + 3] + vb;
;           o[j] = pack2(xa * ya, xb * yb);
;         }
;         uint4 ou; ou.x = o[0]; ou.y = o[1]; ou.z = o[2]; ou.w = o[3];
;         *(uint4*)(Vl + (8 + m1 * 8 + b) * 80 + m2) = ou;
	v_lshlrev_b32_e32 v66, 16, v29
	v_and_b32_e32 v29, 0xffff0000, v29
	v_lshlrev_b32_e32 v35, 16, v35
	v_mul_f32_e32 v60, v11, v19
	v_mul_f32_e32 v62, v5, v23
	v_lshlrev_b32_e32 v63, 16, v24
	v_and_b32_e32 v24, 0xffff0000, v24
	v_lshlrev_b32_e32 v64, 16, v28
	v_and_b32_e32 v28, 0xffff0000, v28
	v_lshlrev_b32_e32 v67, 16, v26
	v_and_b32_e32 v26, 0xffff0000, v26
	v_lshlrev_b32_e32 v68, 16, v30
	v_and_b32_e32 v30, 0xffff0000, v30
	v_lshlrev_b32_e32 v69, 16, v27
	v_and_b32_e32 v27, 0xffff0000, v27
	v_lshlrev_b32_e32 v70, 16, v31
	v_and_b32_e32 v31, 0xffff0000, v31
	v_mul_f32_e32 v15, v3, v15
	v_fmac_f32_e32 v49, v3, v40
	v_mul_f32_e32 v33, v13, v33
	v_fmac_f32_e32 v50, v13, v42
	v_fmac_f32_e32 v51, v3, v16
	v_fmac_f32_e32 v52, v3, v43
	v_fmac_f32_e32 v53, v13, v20
	v_fmac_f32_e32 v54, v13, v44
	v_fmac_f32_e32 v55, v3, v17
	v_fmac_f32_e32 v56, v3, v45
	v_fmac_f32_e32 v57, v13, v21
	v_fmac_f32_e32 v58, v13, v46
	v_fmac_f32_e32 v59, v3, v18
	v_fmac_f32_e32 v61, v13, v22
	v_mul_f32_e32 v41, v125, v41
	v_mul_f32_e32 v38, v125, v38
	v_mul_f32_e32 v73, v11, v65
	v_mul_f32_e32 v74, v11, v25
	v_mul_f32_e32 v75, v5, v66
	v_mul_f32_e32 v76, v5, v29
	v_mul_f32_e32 v35, v126, v35
	v_mul_f32_e32 v37, v126, v37
	v_lshlrev_b32_e32 v39, 16, v39
	v_lshlrev_b32_e32 v36, 16, v36
	v_fmac_f32_e32 v60, v3, v47
	v_fmac_f32_e32 v62, v13, v48
	v_mul_f32_e32 v71, v11, v24
	v_mul_f32_e32 v72, v5, v28
	v_mul_f32_e32 v77, v11, v67
	v_mul_f32_e32 v78, v11, v26
	v_mul_f32_e32 v79, v5, v68
	v_mul_f32_e32 v80, v5, v30
	v_mul_f32_e32 v81, v11, v69
	v_mul_f32_e32 v82, v11, v27
	v_mul_f32_e32 v83, v5, v70
	v_mul_f32_e32 v84, v5, v31
	v_fmac_f32_e32 v15, v11, v40
	v_fmac_f32_e32 v49, v12, v43
	v_fmac_f32_e32 v33, v5, v42
	v_fmac_f32_e32 v50, v10, v44
	v_fmac_f32_e32 v51, v12, v17
	v_fmac_f32_e32 v52, v12, v45
	v_fmac_f32_e32 v53, v10, v21
	v_fmac_f32_e32 v54, v10, v46
	v_fmac_f32_e32 v55, v12, v18
	v_fmac_f32_e32 v56, v12, v47
	v_fmac_f32_e32 v57, v10, v22
	v_fmac_f32_e32 v58, v10, v48
	v_fmac_f32_e32 v59, v12, v19
	v_fmac_f32_e32 v61, v10, v23
	v_mul_f32_e32 v21, v3, v41
	v_mul_f32_e32 v22, v13, v38
	v_fmac_f32_e32 v73, v3, v24
	v_fmac_f32_e32 v74, v3, v65
	v_fmac_f32_e32 v75, v13, v28
	v_fmac_f32_e32 v76, v13, v66
	v_mul_f32_e32 v39, v126, v39
	v_mul_f32_e32 v36, v126, v36
	v_fmac_f32_e32 v60, v12, v35
	v_fmac_f32_e32 v62, v10, v37
	v_fmac_f32_e32 v71, v3, v63
	v_fmac_f32_e32 v72, v13, v64
	v_fmac_f32_e32 v77, v3, v25
	v_fmac_f32_e32 v78, v3, v67
	v_fmac_f32_e32 v79, v13, v29
	v_fmac_f32_e32 v80, v13, v68
	v_fmac_f32_e32 v81, v3, v26
	v_fmac_f32_e32 v82, v3, v69
	v_fmac_f32_e32 v83, v13, v30
	v_fmac_f32_e32 v84, v13, v70
	v_fmac_f32_e32 v15, v12, v16
	v_add_f32_e32 v16, v4, v49
	v_fmac_f32_e32 v33, v10, v20
	v_add_f32_e32 v17, v14, v50
	v_add_f32_e32 v18, v4, v51
	v_add_f32_e32 v19, v4, v52
	v_add_f32_e32 v20, v14, v53
	v_add_f32_e32 v23, v14, v54
	v_add_f32_e32 v35, v4, v55
	v_add_f32_e32 v37, v4, v56
	v_add_f32_e32 v38, v14, v57
	v_add_f32_e32 v40, v14, v58
	v_add_f32_e32 v41, v4, v59
	v_add_f32_e32 v43, v14, v61
	v_fmac_f32_e32 v21, v11, v63
	v_fmac_f32_e32 v22, v5, v64
	v_fmac_f32_e32 v73, v12, v25
	v_fmac_f32_e32 v74, v12, v67
	v_fmac_f32_e32 v75, v10, v29
	v_fmac_f32_e32 v76, v10, v68
	v_add_f32_e32 v42, v4, v60
	v_add_f32_e32 v44, v14, v62
	v_fmac_f32_e32 v71, v12, v65
	v_fmac_f32_e32 v72, v10, v66
	v_fmac_f32_e32 v77, v12, v26
	v_fmac_f32_e32 v78, v12, v69
	v_fmac_f32_e32 v79, v10, v30
	v_fmac_f32_e32 v80, v10, v70
	v_fmac_f32_e32 v81, v12, v27
	v_fmac_f32_e32 v82, v12, v39
	v_fmac_f32_e32 v83, v10, v31
	v_fmac_f32_e32 v84, v10, v36
	v_add_f32_e32 v15, v4, v15
	v_add_f32_e32 v25, v14, v33
	v_mul_f32_e32 v16, v16, v17
	v_mul_f32_e32 v17, v18, v20
	v_mul_f32_e32 v18, v19, v23
	v_mul_f32_e32 v19, v35, v38
	v_mul_f32_e32 v20, v37, v40
	v_mul_f32_e32 v23, v41, v43
	v_fmac_f32_e32 v21, v12, v24
	v_fmac_f32_e32 v22, v10, v28
	v_add_f32_e32 v28, v4, v73
	v_add_f32_e32 v29, v4, v74
	v_add_f32_e32 v30, v14, v75
	v_add_f32_e32 v31, v14, v76
	v_mul_f32_e32 v26, v42, v44
	v_add_f32_e32 v24, v4, v71
	v_add_f32_e32 v27, v14, v72
	v_add_f32_e32 v33, v4, v77
	v_add_f32_e32 v35, v4, v78
	v_add_f32_e32 v36, v14, v79
	v_add_f32_e32 v37, v14, v80
	v_add_f32_e32 v38, v4, v81
	v_add_f32_e32 v39, v4, v82
	v_add_f32_e32 v40, v14, v83
	v_add_f32_e32 v41, v14, v84
	v_mul_f32_e32 v15, v15, v25
	v_cvt_pk_bf16_f32 v17, v17, v18
	v_cvt_pk_bf16_f32 v18, v19, v20
	v_cvt_pk_bf16_f32 v19, v23, v26
	v_add_f32_e32 v20, v4, v21
	v_add_f32_e32 v21, v14, v22
	v_mul_f32_e32 v22, v28, v30
	v_mul_f32_e32 v23, v29, v31
	v_mul_f32_e32 v24, v24, v27
	v_mul_f32_e32 v25, v33, v36
	v_mul_f32_e32 v26, v35, v37
	v_mul_f32_e32 v27, v38, v40
	v_mul_f32_e32 v28, v39, v41
	v_cvt_pk_bf16_f32 v16, v15, v16
	v_mul_f32_e32 v15, v20, v21
	v_cvt_pk_bf16_f32 v21, v22, v23
	v_cvt_pk_bf16_f32 v22, v25, v26
	v_cvt_pk_bf16_f32 v23, v27, v28
	ds_write_b128 v32, v[16:19] offset:33024
	v_cvt_pk_bf16_f32 v20, v15, v24
	ds_write_b128 v34, v[20:23] offset:33024
	s_waitcnt vmcnt(11)
	v_lshlrev_b32_e32 v155, 16, v155
	s_waitcnt vmcnt(10)
	v_lshlrev_b32_e32 v173, 16, v173
	v_mul_f32_e32 v155, v125, v155
	s_waitcnt vmcnt(8)
	v_lshlrev_b32_e32 v177, 16, v180
	s_waitcnt vmcnt(7)
	v_lshlrev_b32_e32 v180, 16, v156
	v_and_b32_e32 v156, 0xffff0000, v156
	s_waitcnt vmcnt(6)
; __device__ __forceinline__ unsigned pack2(float a, float b) { unsigned r; asm("v_cvt_pk_bf16_f32 %0, %1, %2" : "=v"(r) : "v"(a), "v"(b)); return r; }
; __device__ __forceinline__ void phase_hyconv(CP& p, char* smem) {
;     ...
;         for (int j = 0; j < 4; ++j) {
;           const float xa = a0 * e2[2 * j] + a1 * e2[2 * j + 1] + a2 * e2[2 * j + 2] + ab;
;           const float xb = a0 * e2[2 * j + 1] + a1 * e2[2 * j + 2] + a2 * e2[2 * j + 3] + ab;
;           const float ya = v0 * ev[2 * j] + v1 * ev[2 * j + 1] + v2 * ev[2 * j + 2] + vb;
;           const float yb = v0 * ev[2 * j + 1] + v1 * ev[2 * j + 2] + v2 * ev[2 * j + 3] + vb;
;           o[j] = pack2(xa * ya, xb * yb);
;         }
;         uint4 ou; ou.x = o[0]; ou.y = o[1]; ou.z = o[2]; ou.w = o[3];
;         *(uint4*)(Vl + (8 + m1 * 8 + b) * 80 + m2) = ou;
;       }
;     }
;     if (tid < 144) {
;       const int colp = tid / 9, part = tid - colp * 9;
;       const int col = colp < 8 ? colp : 256 + colp;
;       uint4 zz; zz.x = 0; zz.y = 0; zz.z = 0; zz.w = 0;
;       *(uint4*)(Vl + col * 80 + part * 8) = zz;
;     }
;     __syncthreads();
; #pragma unroll
;     for (int s = 1; s < 4; ++s)
; #pragma unroll
;       for (int i = 0; i < 2; ++i) {
;         const int ch = tid + 256 * i;
;         unsigned e[8];
; #pragma unroll
;         for (int j = 0; j < 8; ++j) { const int idx = 8 * ch + s + j; e[j] = idx < 4096 ? (unsigned)cp[idx] : 0u; }
	v_lshlrev_b32_e32 v182, 16, v160
	v_and_b32_e32 v160, 0xffff0000, v160
	v_lshlrev_b32_e32 v183, 16, v157
	v_and_b32_e32 v157, 0xffff0000, v157
	v_lshlrev_b32_e32 v184, 16, v161
	v_and_b32_e32 v161, 0xffff0000, v161
	v_lshlrev_b32_e32 v185, 16, v158
	v_and_b32_e32 v158, 0xffff0000, v158
	v_lshlrev_b32_e32 v186, 16, v162
	v_and_b32_e32 v162, 0xffff0000, v162
	v_lshlrev_b32_e32 v187, 16, v159
	v_lshlrev_b32_e32 v188, 16, v163
	v_and_b32_e32 v159, 0xffff0000, v159
	v_and_b32_e32 v163, 0xffff0000, v163
	v_mul_f32_e32 v173, v125, v173
	v_mul_f32_e32 v189, v11, v156
	v_mul_f32_e32 v190, v5, v160
	v_mul_f32_e32 v191, v11, v183
	v_mul_f32_e32 v192, v11, v157
	v_mul_f32_e32 v193, v5, v184
	v_mul_f32_e32 v194, v5, v161
	v_mul_f32_e32 v195, v11, v185
	v_mul_f32_e32 v196, v11, v158
	v_mul_f32_e32 v197, v5, v186
	v_mul_f32_e32 v198, v5, v162
	v_mul_f32_e32 v199, v11, v187
	v_mul_f32_e32 v201, v5, v188
	s_waitcnt vmcnt(5)
	v_lshlrev_b32_e32 v181, 16, v181
	s_waitcnt vmcnt(4)
	v_lshlrev_b32_e32 v178, 16, v178
	s_waitcnt vmcnt(1)
	v_lshlrev_b32_e32 v205, 16, v165
	v_and_b32_e32 v165, 0xffff0000, v165
	s_waitcnt vmcnt(0)
	v_lshlrev_b32_e32 v206, 16, v169
	v_and_b32_e32 v169, 0xffff0000, v169
	v_lshlrev_b32_e32 v175, 16, v175
	v_mul_f32_e32 v200, v11, v159
	v_mul_f32_e32 v202, v5, v163
	v_lshlrev_b32_e32 v203, 16, v164
	v_and_b32_e32 v164, 0xffff0000, v164
	v_lshlrev_b32_e32 v204, 16, v168
	v_and_b32_e32 v168, 0xffff0000, v168
	v_lshlrev_b32_e32 v207, 16, v166
	v_and_b32_e32 v166, 0xffff0000, v166
	v_lshlrev_b32_e32 v208, 16, v170
	v_and_b32_e32 v170, 0xffff0000, v170
	v_lshlrev_b32_e32 v209, 16, v167
	v_and_b32_e32 v167, 0xffff0000, v167
	v_lshlrev_b32_e32 v210, 16, v171
	v_and_b32_e32 v171, 0xffff0000, v171
	v_mul_f32_e32 v155, v3, v155
	v_fmac_f32_e32 v189, v3, v180
	v_mul_f32_e32 v173, v13, v173
	v_fmac_f32_e32 v190, v13, v182
	v_fmac_f32_e32 v191, v3, v156
	v_fmac_f32_e32 v192, v3, v183
	v_fmac_f32_e32 v193, v13, v160
	v_fmac_f32_e32 v194, v13, v184
	v_fmac_f32_e32 v195, v3, v157
	v_fmac_f32_e32 v196, v3, v185
	v_fmac_f32_e32 v197, v13, v161
	v_fmac_f32_e32 v198, v13, v186
	v_fmac_f32_e32 v199, v3, v158
	v_fmac_f32_e32 v201, v13, v162
	v_mul_f32_e32 v181, v125, v181
	v_mul_f32_e32 v178, v125, v178
	v_mul_f32_e32 v213, v11, v205
	v_mul_f32_e32 v214, v11, v165
	v_mul_f32_e32 v215, v5, v206
	v_mul_f32_e32 v216, v5, v169
	v_mul_f32_e32 v175, v126, v175
	v_mul_f32_e32 v177, v126, v177
	v_lshlrev_b32_e32 v179, 16, v179
	v_lshlrev_b32_e32 v176, 16, v176
	v_fmac_f32_e32 v200, v3, v187
	v_fmac_f32_e32 v202, v13, v188
	v_mul_f32_e32 v211, v11, v164
	v_mul_f32_e32 v212, v5, v168
	v_mul_f32_e32 v217, v11, v207
	v_mul_f32_e32 v218, v11, v166
	v_mul_f32_e32 v219, v5, v208
	v_mul_f32_e32 v220, v5, v170
	v_mul_f32_e32 v221, v11, v209
	v_mul_f32_e32 v222, v11, v167
	v_mul_f32_e32 v223, v5, v210
	v_mul_f32_e32 v224, v5, v171
	v_fmac_f32_e32 v155, v11, v180
	v_fmac_f32_e32 v189, v12, v183
	v_fmac_f32_e32 v173, v5, v182
	v_fmac_f32_e32 v190, v10, v184
	v_fmac_f32_e32 v191, v12, v157
	v_fmac_f32_e32 v192, v12, v185
	v_fmac_f32_e32 v193, v10, v161
	v_fmac_f32_e32 v194, v10, v186
	v_fmac_f32_e32 v195, v12, v158
	v_fmac_f32_e32 v196, v12, v187
	v_fmac_f32_e32 v197, v10, v162
	v_fmac_f32_e32 v198, v10, v188
	v_fmac_f32_e32 v199, v12, v159
	v_fmac_f32_e32 v201, v10, v163
	v_mul_f32_e32 v161, v3, v181
	v_mul_f32_e32 v162, v13, v178
	v_fmac_f32_e32 v213, v3, v164
	v_fmac_f32_e32 v214, v3, v205
	v_fmac_f32_e32 v215, v13, v168
	v_fmac_f32_e32 v216, v13, v206
	v_mul_f32_e32 v179, v126, v179
	v_mul_f32_e32 v176, v126, v176
	v_fmac_f32_e32 v200, v12, v175
	v_fmac_f32_e32 v202, v10, v177
	v_fmac_f32_e32 v211, v3, v203
	v_fmac_f32_e32 v212, v13, v204
	v_fmac_f32_e32 v217, v3, v165
	v_fmac_f32_e32 v218, v3, v207
	v_fmac_f32_e32 v219, v13, v169
	v_fmac_f32_e32 v220, v13, v208
	v_fmac_f32_e32 v221, v3, v166
	v_fmac_f32_e32 v222, v3, v209
	v_fmac_f32_e32 v223, v13, v170
	v_fmac_f32_e32 v224, v13, v210
	v_fmac_f32_e32 v155, v12, v156
	v_add_f32_e32 v156, v4, v189
	v_fmac_f32_e32 v173, v10, v160
	v_add_f32_e32 v157, v14, v190
	v_add_f32_e32 v158, v4, v191
	v_add_f32_e32 v159, v4, v192
	v_add_f32_e32 v160, v14, v193
	v_add_f32_e32 v163, v14, v194
	v_add_f32_e32 v175, v4, v195
	v_add_f32_e32 v177, v4, v196
	v_add_f32_e32 v178, v14, v197
	v_add_f32_e32 v180, v14, v198
	v_add_f32_e32 v181, v4, v199
	v_add_f32_e32 v183, v14, v201
	v_fmac_f32_e32 v161, v11, v203
	v_fmac_f32_e32 v162, v5, v204
	v_fmac_f32_e32 v213, v12, v165
	v_fmac_f32_e32 v214, v12, v207
	v_fmac_f32_e32 v215, v10, v169
	v_fmac_f32_e32 v216, v10, v208
	v_add_f32_e32 v182, v4, v200
	v_add_f32_e32 v184, v14, v202
	v_fmac_f32_e32 v211, v12, v205
	v_fmac_f32_e32 v212, v10, v206
	v_fmac_f32_e32 v217, v12, v166
	v_fmac_f32_e32 v218, v12, v209
	v_fmac_f32_e32 v219, v10, v170
	v_fmac_f32_e32 v220, v10, v210
	v_fmac_f32_e32 v221, v12, v167
	v_fmac_f32_e32 v222, v12, v179
	v_fmac_f32_e32 v223, v10, v171
	v_fmac_f32_e32 v224, v10, v176
	v_add_f32_e32 v155, v4, v155
	v_add_f32_e32 v165, v14, v173
	v_mul_f32_e32 v156, v156, v157
	v_mul_f32_e32 v157, v158, v160
	v_mul_f32_e32 v158, v159, v163
	v_mul_f32_e32 v159, v175, v178
	v_mul_f32_e32 v160, v177, v180
	v_mul_f32_e32 v163, v181, v183
	v_fmac_f32_e32 v161, v12, v164
	v_fmac_f32_e32 v162, v10, v168
	v_add_f32_e32 v168, v4, v213
	v_add_f32_e32 v169, v4, v214
	v_add_f32_e32 v170, v14, v215
	v_add_f32_e32 v171, v14, v216
	v_mul_f32_e32 v166, v182, v184
	v_add_f32_e32 v164, v4, v211
	v_add_f32_e32 v167, v14, v212
	v_add_f32_e32 v173, v4, v217
	v_add_f32_e32 v175, v4, v218
	v_add_f32_e32 v176, v14, v219
	v_add_f32_e32 v177, v14, v220
	v_add_f32_e32 v178, v4, v221
	v_add_f32_e32 v179, v4, v222
	v_add_f32_e32 v180, v14, v223
	v_add_f32_e32 v181, v14, v224
	v_mul_f32_e32 v155, v155, v165
	v_cvt_pk_bf16_f32 v157, v157, v158
	v_cvt_pk_bf16_f32 v158, v159, v160
	v_cvt_pk_bf16_f32 v159, v163, v166
	v_add_f32_e32 v160, v4, v161
	v_add_f32_e32 v161, v14, v162
	v_mul_f32_e32 v162, v168, v170
	v_mul_f32_e32 v163, v169, v171
	v_mul_f32_e32 v164, v164, v167
	v_mul_f32_e32 v165, v173, v176
	v_mul_f32_e32 v166, v175, v177
	v_mul_f32_e32 v167, v178, v180
	v_mul_f32_e32 v168, v179, v181
	v_cvt_pk_bf16_f32 v156, v155, v156
	v_mul_f32_e32 v155, v160, v161
	v_cvt_pk_bf16_f32 v161, v162, v163
	v_cvt_pk_bf16_f32 v162, v165, v166
	v_cvt_pk_bf16_f32 v163, v167, v168
	ds_write_b128 v172, v[156:159] offset:33024
	v_cvt_pk_bf16_f32 v160, v155, v164
	ds_write_b128 v174, v[160:163] offset:33024
	s_and_saveexec_b64 s[46:47], vcc
	ds_write_b128 v139, v[6:9] offset:33024
	s_or_b64 exec, exec, s[46:47]
	v_mov_b32_e32 v4, 0
	v_mov_b32_e32 v3, 0
	s_waitcnt lgkmcnt(0)
	s_barrier
	s_and_saveexec_b64 s[46:47], s[4:5]
	ds_read_u16 v3, v130 offset:2
	s_or_b64 exec, exec, s[46:47]
	s_and_saveexec_b64 s[46:47], s[6:7]
	s_cbranch_execz .LBB0_2859
	ds_read_u16 v4, v130 offset:4
	s_waitcnt lgkmcnt(0)
	v_lshlrev_b32_e32 v4, 16, v4
